# norm_rows (prep, final): gain loads issued together with the row loads instead of one store-load-wait per 16B
# baseline (speedup 1.0000x reference)
; __device__ __forceinline__ unsigned pk2(float lo, float hi) { const f32x2 v = {lo, hi}; const bf16v2 b = __builtin_convertvector(v, bf16v2); return __builtin_bit_cast(unsigned, b); }
; #define p (*kparams())
; __device__ __forceinline__ void norm_rows(CParams& p, int mode, const float* gain, int nrows) {
;     ...
;         float s = 0.f;
; #pragma unroll
;         for (int j = 0; j < 8; ++j) s += (v[j][0] * v[j][0] + v[j][1] * v[j][1]) + (v[j][2] * v[j][2] + v[j][3] * v[j][3]);
;         const float rs = 1.0f / sqrtf(wave_sum(s) * (1.0f / D) + EPS);
; #pragma unroll
;         for (int j = 0; j < 8; ++j) {
;             const f32x4 g = *(const f32x4*)(gain + (lane + 64 * j) * 4);
;             const f32x4 y = v[j] * rs * g;
;             if (mode == 3) *(f32x4*)(p.out + (size_t)row * D + (lane + 64 * j) * 4) = y;
;             else { u32x2 w; w.x = pk2(y[0], y[1]); w.y = pk2(y[2], y[3]); *(u32x2*)(NB + (size_t)row * D + (lane + 64 * j) * 4) = w; }
;         }
.LBB0_99:
	global_load_dwordx4 v[120:123], v[40:41], off
	global_load_dwordx4 v[124:127], v[40:41], off offset:1024
	global_load_dwordx4 v[128:131], v[40:41], off offset:2048
	global_load_dwordx4 v[132:135], v[40:41], off offset:3072
	global_load_dwordx4 v[136:139], v[42:43], off
	global_load_dwordx4 v[140:143], v[44:45], off
	global_load_dwordx4 v[144:147], v[46:47], off
	global_load_dwordx4 v[148:151], v[48:49], off
	s_waitcnt vmcnt(0)
	v_pk_mul_f32 v[74:75], v[4:5], v[4:5]
	v_pk_mul_f32 v[76:77], v[8:9], v[8:9]
	v_pk_mul_f32 v[70:71], v[6:7], v[6:7]
	v_pk_mul_f32 v[72:73], v[10:11], v[10:11]
	v_mov_b32_e32 v78, v74
	v_mov_b32_e32 v79, v76
	v_mov_b32_e32 v76, v75
	v_pk_mul_f32 v[60:61], v[14:15], v[14:15]
	v_pk_mul_f32 v[68:69], v[12:13], v[12:13]
	v_pk_add_f32 v[74:75], v[78:79], v[76:77]
	v_mov_b32_e32 v76, v70
	v_mov_b32_e32 v77, v72
	v_mov_b32_e32 v72, v71
	v_pk_add_f32 v[70:71], v[76:77], v[72:73]
	v_pk_mov_b32 v[72:73], v[68:69], v[60:61] op_sel:[1,0]
	v_mov_b32_e32 v69, v61
	v_pk_add_f32 v[60:61], v[72:73], v[68:69]
	v_pk_add_f32 v[70:71], v[74:75], v[70:71]
	v_pk_add_f32 v[60:61], v[60:61], v[60:61] op_sel_hi:[0,1]
	v_mul_f32_e32 v60, v16, v16
	v_pk_fma_f32 v[68:69], v[16:17], v[16:17], v[60:61] op_sel_hi:[1,1,0]
	v_mul_f32_e32 v60, v18, v18
	v_pk_add_f32 v[70:71], v[70:71], v[70:71] op_sel_hi:[0,1]
	v_pk_fma_f32 v[72:73], v[18:19], v[18:19], v[60:61] op_sel_hi:[1,1,0]
	v_mul_f32_e32 v68, v20, v20
	v_mul_f32_e32 v72, v21, v21
	v_mul_f32_e32 v60, v22, v22
	v_mul_f32_e32 v70, v23, v23
	v_pk_mul_f32 v[56:57], v[26:27], v[26:27]
	v_pk_mul_f32 v[58:59], v[24:25], v[24:25]
	v_pk_add_f32 v[68:69], v[68:69], v[72:73]
	v_pk_add_f32 v[60:61], v[60:61], v[70:71]
	v_lshlrev_b64 v[0:1], 12, v[0:1]
	v_pk_add_f32 v[60:61], v[68:69], v[60:61]
	v_pk_mov_b32 v[68:69], v[58:59], v[56:57] op_sel:[1,0]
	v_mov_b32_e32 v59, v57
	v_pk_add_f32 v[56:57], v[68:69], v[58:59]
	v_pk_add_f32 v[60:61], v[60:61], v[60:61] op_sel_hi:[0,1]
	v_pk_add_f32 v[68:69], v[56:57], v[56:57] op_sel_hi:[0,1]
	v_mul_f32_e32 v56, v28, v28
	v_pk_fma_f32 v[56:57], v[28:29], v[28:29], v[56:57] op_sel_hi:[1,1,0]
	v_mul_f32_e32 v68, v34, v34
	v_mul_f32_e32 v56, v30, v30
	v_pk_fma_f32 v[58:59], v[30:31], v[30:31], v[56:57] op_sel_hi:[1,1,0]
	v_mul_f32_e32 v56, v32, v32
	v_mul_f32_e32 v58, v33, v33
	v_pk_add_f32 v[70:71], v[56:57], v[58:59]
	v_mul_f32_e32 v60, v35, v35
	v_pk_add_f32 v[60:61], v[68:69], v[60:61]
	v_lshl_add_u64 v[0:1], v[52:53], 0, v[0:1]
	v_pk_add_f32 v[60:61], v[70:71], v[60:61]
	v_lshl_add_u64 v[36:37], v[36:37], 0, s[28:29]
	v_add_f32_e32 v3, v60, v61
	ds_bpermute_b32 v60, v39, v3
	s_add_u32 s48, s48, s60
	s_movk_i32 s6, 0x40ff
	s_addc_u32 s49, s49, s61
	v_lshl_add_u64 v[50:51], v[50:51], 0, s[60:61]
	s_waitcnt lgkmcnt(0)
	v_add_f32_e32 v3, v3, v60
	ds_bpermute_b32 v60, v62, v3
	s_waitcnt lgkmcnt(0)
	v_add_f32_e32 v3, v3, v60
	ds_bpermute_b32 v60, v63, v3
	s_waitcnt lgkmcnt(0)
	v_add_f32_e32 v3, v3, v60
	ds_bpermute_b32 v60, v64, v3
	s_waitcnt lgkmcnt(0)
	v_add_f32_e32 v3, v3, v60
	ds_bpermute_b32 v60, v65, v3
	s_waitcnt lgkmcnt(0)
	v_add_f32_e32 v3, v3, v60
	ds_bpermute_b32 v60, v66, v3
	s_waitcnt lgkmcnt(0)
	v_add_f32_e32 v3, v3, v60
	v_fmamk_f32 v3, v3, 0x3a000000, v208
	v_mul_f32_e32 v60, 0x4f800000, v3
	v_cmp_gt_f32_e32 vcc, s88, v3
	s_nop 1
	v_cndmask_b32_e32 v3, v3, v60, vcc
	v_sqrt_f32_e32 v60, v3
	s_nop 0
	v_add_u32_e32 v61, -1, v60
	v_fma_f32 v67, -v61, v60, v3
	v_cmp_ge_f32_e64 s[42:43], 0, v67
	v_add_u32_e32 v67, 1, v60
	s_nop 0
	v_cndmask_b32_e64 v61, v60, v61, s[42:43]
	v_fma_f32 v60, -v67, v60, v3
	v_cmp_lt_f32_e64 s[42:43], 0, v60
	s_nop 1
	v_cndmask_b32_e64 v60, v61, v67, s[42:43]
	v_mul_f32_e32 v61, 0x37800000, v60
	v_cndmask_b32_e32 v60, v60, v61, vcc
	v_cmp_class_f32_e32 vcc, v3, v209
	s_nop 1
	v_cndmask_b32_e32 v3, v60, v3, vcc
	v_div_scale_f32 v60, s[8:9], v3, v3, 1.0
	v_rcp_f32_e32 v61, v60
	s_nop 0
	v_fma_f32 v67, -v60, v61, 1.0
	v_fmac_f32_e32 v61, v67, v61
	v_div_scale_f32 v67, vcc, 1.0, v3, 1.0
	v_mul_f32_e32 v68, v67, v61
	v_fma_f32 v69, -v60, v68, v67
	v_fmac_f32_e32 v68, v69, v61
	v_fma_f32 v60, -v60, v68, v67
	v_div_fmas_f32 v60, v60, v61, v68
	v_div_fixup_f32 v60, v60, v3, 1.0
	v_pk_mul_f32 v[4:5], v[4:5], v[60:61] op_sel_hi:[1,0]
	v_pk_mul_f32 v[6:7], v[6:7], v[60:61] op_sel_hi:[1,0]
	v_pk_mul_f32 v[4:5], v[120:121], v[4:5]
	v_pk_mul_f32 v[6:7], v[122:123], v[6:7]
	v_cvt_pk_bf16_f32 v4, v4, v5
	v_cvt_pk_bf16_f32 v5, v6, v7
	global_store_dwordx2 v[0:1], v[4:5], off
	v_pk_mul_f32 v[8:9], v[8:9], v[60:61] op_sel_hi:[1,0]
	v_pk_mul_f32 v[10:11], v[10:11], v[60:61] op_sel_hi:[1,0]
	v_cmp_lt_i32_e32 vcc, s6, v36
	s_or_b64 s[62:63], vcc, s[62:63]
	v_pk_mul_f32 v[6:7], v[126:127], v[10:11]
	v_pk_mul_f32 v[4:5], v[124:125], v[8:9]
	v_pk_mul_f32 v[8:9], v[12:13], v[60:61] op_sel_hi:[1,0]
	v_cvt_pk_bf16_f32 v4, v4, v5
	v_cvt_pk_bf16_f32 v5, v6, v7
	global_store_dwordx2 v[0:1], v[4:5], off offset:512
	v_pk_mul_f32 v[10:11], v[14:15], v[60:61] op_sel_hi:[1,0]
	v_pk_mul_f32 v[4:5], v[128:129], v[8:9]
	v_pk_mul_f32 v[6:7], v[130:131], v[10:11]
	v_cvt_pk_bf16_f32 v4, v4, v5
	v_cvt_pk_bf16_f32 v5, v6, v7
	global_store_dwordx2 v[0:1], v[4:5], off offset:1024
	v_pk_mul_f32 v[8:9], v[16:17], v[60:61] op_sel_hi:[1,0]
	v_pk_mul_f32 v[10:11], v[18:19], v[60:61] op_sel_hi:[1,0]
	v_pk_mul_f32 v[4:5], v[132:133], v[8:9]
	v_pk_mul_f32 v[6:7], v[134:135], v[10:11]
	v_cvt_pk_bf16_f32 v4, v4, v5
	v_cvt_pk_bf16_f32 v5, v6, v7
	global_store_dwordx2 v[0:1], v[4:5], off offset:1536
	v_pk_mul_f32 v[8:9], v[20:21], v[60:61] op_sel_hi:[1,0]
	v_pk_mul_f32 v[10:11], v[22:23], v[60:61] op_sel_hi:[1,0]
	v_pk_mul_f32 v[4:5], v[136:137], v[8:9]
	v_pk_mul_f32 v[6:7], v[138:139], v[10:11]
	v_cvt_pk_bf16_f32 v4, v4, v5
	v_cvt_pk_bf16_f32 v5, v6, v7
	global_store_dwordx2 v[0:1], v[4:5], off offset:2048
	v_pk_mul_f32 v[8:9], v[24:25], v[60:61] op_sel_hi:[1,0]
	v_pk_mul_f32 v[10:11], v[26:27], v[60:61] op_sel_hi:[1,0]
	v_pk_mul_f32 v[4:5], v[140:141], v[8:9]
	v_pk_mul_f32 v[6:7], v[142:143], v[10:11]
	v_cvt_pk_bf16_f32 v4, v4, v5
	v_cvt_pk_bf16_f32 v5, v6, v7
	global_store_dwordx2 v[0:1], v[4:5], off offset:2560
	v_pk_mul_f32 v[8:9], v[28:29], v[60:61] op_sel_hi:[1,0]
	v_pk_mul_f32 v[10:11], v[30:31], v[60:61] op_sel_hi:[1,0]
	v_pk_mul_f32 v[4:5], v[144:145], v[8:9]
	v_pk_mul_f32 v[6:7], v[146:147], v[10:11]
	v_cvt_pk_bf16_f32 v4, v4, v5
	v_cvt_pk_bf16_f32 v5, v6, v7
	global_store_dwordx2 v[0:1], v[4:5], off offset:3072
	v_pk_mul_f32 v[8:9], v[32:33], v[60:61] op_sel_hi:[1,0]
	v_pk_mul_f32 v[10:11], v[34:35], v[60:61] op_sel_hi:[1,0]
	v_pk_mul_f32 v[4:5], v[148:149], v[8:9]
	v_pk_mul_f32 v[6:7], v[150:151], v[10:11]
	v_cvt_pk_bf16_f32 v4, v4, v5
	v_cvt_pk_bf16_f32 v5, v6, v7
	global_store_dwordx2 v[0:1], v[4:5], off offset:3584
	s_nop 1
	v_mov_b32_e32 v56, v120
	v_mov_b32_e32 v57, v121
	v_mov_b32_e32 v58, v122
	v_mov_b32_e32 v59, v123
	s_andn2_b64 exec, exec, s[62:63]
	s_cbranch_execz .LBB0_9
